# SGU prompt unit: W/U staging loads batched at unit top, epilogue gate/bias loads prefetched before barrier
# speedup vs baseline: 1.0005x; 1.0005x over previous
.LBB0_303:
	v_readlane_b32 s4, v255, 10
	v_readlane_b32 s5, v255, 11
	s_andn2_b64 vcc, exec, s[4:5]
	s_cbranch_vccnz .LBB0_305
	s_mov_b64 s[10:11], s[94:95]
	s_add_u32 s55, s10, 0xc700000
	s_addc_u32 s64, s11, 0
	s_lshl_b32 s0, s68, 5
	s_and_b32 s52, s68, 3
	s_addk_i32 s0, 0x3000
	s_and_b32 s54, s0, 0x3f80
	s_lshl_b32 s0, s52, 16
	v_lshl_add_u64 v[10:11], v[70:71], 0, s[0:1]
	v_lshl_add_u64 v[4:5], v[72:73], 2, v[10:11]
	global_load_dwordx4 v[0:3], v[4:5], off offset:16
	s_nop 0
	global_load_dwordx4 v[4:7], v[4:5], off
	v_readlane_b32 s4, v255, 12
	v_mov_b32_e32 v8, s1
	v_readlane_b32 s5, v255, 13
	s_mul_i32 s0, s54, 0x2800
	s_add_u32 s66, s55, s0
	s_addc_u32 s67, s64, 0
	s_lshl_b32 s0, s52, 9
	s_add_u32 s52, s66, s0
	s_addc_u32 s53, s67, 0
	s_add_u32 s66, s52, 0x3000
	s_addc_u32 s67, s53, 0
	v_lshl_add_u64 v[30:31], v[74:75], 2, v[10:11]
	global_load_dwordx4 v[14:17], v[30:31], off offset:16
	global_load_dwordx4 v[18:21], v[30:31], off
	v_lshl_add_u64 v[32:33], v[76:77], 2, v[10:11]
	global_load_dwordx4 v[22:25], v[32:33], off offset:16
	global_load_dwordx4 v[26:29], v[32:33], off
	v_lshl_add_u64 v[30:31], v[78:79], 2, v[10:11]
	global_load_dwordx4 v[40:43], v[30:31], off offset:16
	global_load_dwordx4 v[44:47], v[30:31], off
	v_lshl_add_u64 v[32:33], v[80:81], 1, s[52:53]
	v_lshl_add_u64 v[32:33], v[82:83], 1, v[32:33]
	global_load_dwordx4 v[48:51], v[32:33], off offset:2048
	v_lshl_add_u64 v[30:31], v[80:81], 1, s[66:67]
	v_lshl_add_u64 v[30:31], v[82:83], 1, v[30:31]
	global_load_dwordx4 v[52:55], v[30:31], off
	v_lshl_add_u64 v[32:33], v[84:85], 1, s[52:53]
	v_lshl_add_u64 v[32:33], v[86:87], 1, v[32:33]
	global_load_dwordx4 v[56:59], v[32:33], off offset:2048
	v_lshl_add_u64 v[30:31], v[84:85], 1, s[66:67]
	v_lshl_add_u64 v[30:31], v[86:87], 1, v[30:31]
	global_load_dwordx4 v[60:63], v[30:31], off
	v_lshl_add_u64 v[32:33], v[88:89], 1, s[52:53]
	v_lshl_add_u64 v[32:33], v[90:91], 1, v[32:33]
	global_load_dwordx4 v[194:197], v[32:33], off offset:2048
	v_lshl_add_u64 v[30:31], v[88:89], 1, s[66:67]
	v_lshl_add_u64 v[30:31], v[90:91], 1, v[30:31]
	global_load_dwordx4 v[198:201], v[30:31], off
	v_lshl_add_u64 v[32:33], v[92:93], 1, s[52:53]
	v_lshl_add_u64 v[32:33], v[94:95], 1, v[32:33]
	global_load_dwordx4 v[202:205], v[32:33], off offset:2048
	v_lshl_add_u64 v[30:31], v[92:93], 1, s[66:67]
	v_lshl_add_u64 v[30:31], v[94:95], 1, v[30:31]
	global_load_dwordx4 v[206:209], v[30:31], off
	v_add_u32_e32 v152, v103, v105
	v_add_u32_e32 v36, v103, v107
	v_readlane_b32 s88, v254, 43
	v_readlane_b32 s92, v254, 25
	v_readlane_b32 s89, v254, 44
	v_readlane_b32 s93, v254, 26
	v_readlane_b32 s94, v254, 27
	v_readlane_b32 s95, v254, 28
	s_waitcnt vmcnt(14)
	v_cndmask_b32_e64 v9, v6, v6, s[4:5]
	v_cndmask_b32_e64 v12, v7, v7, s[4:5]
	v_cndmask_b32_e64 v13, v4, v8, s[4:5]
	v_readlane_b32 s4, v255, 14
	v_readlane_b32 s5, v255, 15
	s_nop 1
	v_cndmask_b32_e64 v8, v0, v8, s[4:5]
	v_cndmask_b32_e64 v0, v3, v3, s[4:5]
	v_cndmask_b32_e64 v2, v2, v2, s[4:5]
	v_cndmask_b32_e64 v1, v1, v1, s[4:5]
	v_readlane_b32 s4, v255, 16
	v_readlane_b32 s5, v255, 17
	s_nop 1
	v_cndmask_b32_e64 v3, v13, v4, s[4:5]
	v_cndmask_b32_e64 v4, v12, v7, s[4:5]
	v_cndmask_b32_e64 v6, v9, v6, s[4:5]
	v_cndmask_b32_e64 v5, 0, v5, s[4:5]
	v_readlane_b32 s4, v255, 18
	v_readlane_b32 s5, v255, 19
	s_nop 1
	v_cndmask_b32_e64 v7, v1, 0, s[4:5]
	v_readlane_b32 s4, v255, 20
	v_readlane_b32 s5, v255, 21
	s_nop 1
	v_cndmask_b32_e64 v1, v6, 0, s[4:5]
	v_readlane_b32 s4, v255, 22
	v_readlane_b32 s5, v255, 23
	s_nop 1
	v_cndmask_b32_e64 v6, v2, 0, s[4:5]
	v_readlane_b32 s4, v255, 24
	v_readlane_b32 s5, v255, 25
	s_nop 1
	v_cndmask_b32_e64 v2, v4, 0, s[4:5]
	v_readlane_b32 s4, v255, 26
	v_readlane_b32 s5, v255, 27
	v_cvt_pk_bf16_f32 v1, v1, v2
	v_cvt_pk_bf16_f32 v2, v8, v7
	v_cndmask_b32_e64 v4, v0, 0, s[4:5]
	v_cvt_pk_bf16_f32 v0, v3, v5
	v_cvt_pk_bf16_f32 v3, v6, v4
	ds_write_b128 v165, v[0:3]
	v_readlane_b32 s4, v255, 28
	v_mov_b32_e32 v8, s1
	v_readlane_b32 s5, v255, 29
	s_waitcnt vmcnt(12)
	v_mov_b64_e32 v[0:1], v[14:15]
	v_mov_b64_e32 v[2:3], v[16:17]
	v_mov_b64_e32 v[4:5], v[18:19]
	v_mov_b64_e32 v[6:7], v[20:21]
	v_cndmask_b32_e64 v1, v1, v1, s[14:15]
	v_cndmask_b32_e64 v9, v6, v6, s[4:5]
	v_cndmask_b32_e64 v12, v7, v7, s[4:5]
	v_cndmask_b32_e64 v13, v4, v8, s[4:5]
	v_readlane_b32 s4, v255, 30
	v_readlane_b32 s5, v255, 31
	v_cndmask_b32_e64 v8, v0, v8, s[14:15]
	v_cndmask_b32_e64 v0, v3, v3, s[14:15]
	v_cndmask_b32_e64 v3, v13, v4, s[6:7]
	v_cndmask_b32_e64 v4, v12, v7, s[6:7]
	v_cndmask_b32_e64 v7, v1, 0, s[4:5]
	v_readlane_b32 s4, v255, 32
	v_cndmask_b32_e64 v6, v9, v6, s[6:7]
	v_readlane_b32 s5, v255, 33
	v_cndmask_b32_e64 v2, v2, v2, s[14:15]
	v_cndmask_b32_e64 v5, 0, v5, s[6:7]
	v_cndmask_b32_e64 v1, v6, 0, s[4:5]
	v_readlane_b32 s4, v254, 59
	v_readlane_b32 s5, v254, 60
	s_nop 1
	v_cndmask_b32_e64 v6, v2, 0, s[4:5]
	v_readlane_b32 s4, v254, 61
	v_readlane_b32 s5, v254, 62
	s_nop 1
	v_cndmask_b32_e64 v2, v4, 0, s[4:5]
	v_readlane_b32 s4, v255, 0
	v_readlane_b32 s5, v255, 1
	v_cvt_pk_bf16_f32 v1, v1, v2
	v_cvt_pk_bf16_f32 v2, v8, v7
	v_cndmask_b32_e64 v4, v0, 0, s[4:5]
	v_cvt_pk_bf16_f32 v0, v3, v5
	v_cvt_pk_bf16_f32 v3, v6, v4
	ds_write_b128 v166, v[0:3]
	v_readlane_b32 s4, v255, 2
	v_mov_b32_e32 v8, s1
	v_readlane_b32 s5, v255, 3
	s_waitcnt vmcnt(10)
	v_mov_b64_e32 v[0:1], v[22:23]
	v_mov_b64_e32 v[2:3], v[24:25]
	v_mov_b64_e32 v[4:5], v[26:27]
	v_mov_b64_e32 v[6:7], v[28:29]
	v_cndmask_b32_e64 v1, v1, v1, s[22:23]
	v_cndmask_b32_e64 v9, v6, v6, s[4:5]
	v_cndmask_b32_e64 v12, v7, v7, s[4:5]
	v_cndmask_b32_e64 v13, v4, v8, s[4:5]
	v_readlane_b32 s4, v255, 4
	v_readlane_b32 s5, v255, 5
	v_cndmask_b32_e64 v8, v0, v8, s[22:23]
	v_cndmask_b32_e64 v0, v3, v3, s[22:23]
	v_cndmask_b32_e64 v3, v13, v4, s[16:17]
	v_cndmask_b32_e64 v4, v12, v7, s[16:17]
	v_cndmask_b32_e64 v7, v1, 0, s[4:5]
	v_readlane_b32 s4, v255, 6
	v_cndmask_b32_e64 v6, v9, v6, s[16:17]
	v_readlane_b32 s5, v255, 7
	v_cndmask_b32_e64 v2, v2, v2, s[22:23]
	v_cndmask_b32_e64 v5, 0, v5, s[16:17]
	v_cndmask_b32_e64 v1, v6, 0, s[4:5]
	v_readlane_b32 s4, v255, 8
	v_readlane_b32 s5, v255, 9
	s_nop 1
	v_cndmask_b32_e64 v6, v2, 0, s[4:5]
	v_readlane_b32 s4, v255, 34
	v_readlane_b32 s5, v255, 35
	s_nop 1
	v_cndmask_b32_e64 v2, v4, 0, s[4:5]
	v_readlane_b32 s4, v255, 36
	v_readlane_b32 s5, v255, 37
	v_cvt_pk_bf16_f32 v1, v1, v2
	v_cvt_pk_bf16_f32 v2, v8, v7
	v_cndmask_b32_e64 v4, v0, 0, s[4:5]
	v_cvt_pk_bf16_f32 v0, v3, v5
	v_cvt_pk_bf16_f32 v3, v6, v4
	ds_write_b128 v167, v[0:3]
	v_readlane_b32 s4, v255, 38
	v_mov_b32_e32 v8, s1
	v_readlane_b32 s5, v255, 39
	s_waitcnt vmcnt(8)
	v_mov_b64_e32 v[0:1], v[40:41]
	v_mov_b64_e32 v[2:3], v[42:43]
	v_mov_b64_e32 v[4:5], v[44:45]
	v_mov_b64_e32 v[6:7], v[46:47]
	v_cndmask_b32_e64 v1, v1, v1, s[90:91]
	v_cndmask_b32_e64 v9, v6, v6, s[4:5]
	v_cndmask_b32_e64 v10, v7, v7, s[4:5]
	v_cndmask_b32_e64 v11, v4, v8, s[4:5]
	v_readlane_b32 s4, v255, 40
	v_readlane_b32 s5, v255, 41
	v_cndmask_b32_e64 v8, v0, v8, s[90:91]
	v_cndmask_b32_e64 v0, v3, v3, s[90:91]
	v_cndmask_b32_e64 v3, v11, v4, s[18:19]
	v_cndmask_b32_e64 v4, v10, v7, s[18:19]
	v_cndmask_b32_e64 v7, v1, 0, s[4:5]
	v_readlane_b32 s4, v255, 42
	v_cndmask_b32_e64 v6, v9, v6, s[18:19]
	v_readlane_b32 s5, v255, 43
	v_cndmask_b32_e64 v2, v2, v2, s[90:91]
	v_cndmask_b32_e64 v5, 0, v5, s[18:19]
	v_cndmask_b32_e64 v1, v6, 0, s[4:5]
	v_readlane_b32 s4, v255, 44
	v_readlane_b32 s5, v255, 45
	v_add_u32_e32 v9, v69, v97
	s_nop 0
	v_cndmask_b32_e64 v6, v2, 0, s[4:5]
	v_readlane_b32 s4, v255, 46
	v_readlane_b32 s5, v255, 47
	s_nop 1
	v_cndmask_b32_e64 v2, v4, 0, s[4:5]
	v_readlane_b32 s4, v255, 48
	v_readlane_b32 s5, v255, 49
	v_cvt_pk_bf16_f32 v1, v1, v2
	v_cvt_pk_bf16_f32 v2, v8, v7
	v_cndmask_b32_e64 v4, v0, 0, s[4:5]
	v_cvt_pk_bf16_f32 v0, v3, v5
	v_cvt_pk_bf16_f32 v3, v6, v4
	ds_write_b128 v168, v[0:3]
	s_waitcnt vmcnt(6)
	v_mov_b64_e32 v[0:1], v[48:49]
	v_mov_b64_e32 v[2:3], v[50:51]
	v_mov_b64_e32 v[4:5], v[52:53]
	v_mov_b64_e32 v[6:7], v[54:55]
	v_and_b32_e32 v8, 0xffff, v0
	v_lshrrev_b32_e32 v0, 16, v0
	v_lshl_or_b32 v8, v4, 16, v8
	v_and_or_b32 v0, v4, s59, v0
	v_add_u32_e32 v4, 0x8800, v9
	ds_write2_b32 v4, v8, v0 offset1:68
	v_and_b32_e32 v0, 0xffff, v1
	v_lshrrev_b32_e32 v1, 16, v1
	v_lshl_or_b32 v0, v5, 16, v0
	v_and_or_b32 v1, v5, s59, v1
	ds_write2_b32 v4, v0, v1 offset0:136 offset1:204
	v_and_b32_e32 v0, 0xffff, v2
	v_lshrrev_b32_e32 v1, 16, v2
	v_lshl_or_b32 v0, v6, 16, v0
	v_and_or_b32 v1, v6, s59, v1
	v_add_u32_e32 v2, 0x8c00, v9
	ds_write2_b32 v2, v0, v1 offset0:16 offset1:84
	v_and_b32_e32 v0, 0xffff, v3
	v_lshrrev_b32_e32 v1, 16, v3
	v_lshl_or_b32 v0, v7, 16, v0
	v_and_or_b32 v1, v7, s59, v1
	ds_write2_b32 v2, v0, v1 offset0:152 offset1:220
	v_add_u32_e32 v9, v99, v101
	s_nop 0
	s_waitcnt vmcnt(4)
	v_mov_b64_e32 v[0:1], v[56:57]
	v_mov_b64_e32 v[2:3], v[58:59]
	v_mov_b64_e32 v[4:5], v[60:61]
	v_mov_b64_e32 v[6:7], v[62:63]
	v_and_b32_e32 v8, 0xffff, v0
	v_lshrrev_b32_e32 v0, 16, v0
	v_lshl_or_b32 v8, v4, 16, v8
	v_and_or_b32 v0, v4, s59, v0
	v_add_u32_e32 v4, 0x8800, v9
	ds_write2_b32 v4, v8, v0 offset1:68
	v_and_b32_e32 v0, 0xffff, v1
	v_lshrrev_b32_e32 v1, 16, v1
	v_lshl_or_b32 v0, v5, 16, v0
	v_and_or_b32 v1, v5, s59, v1
	ds_write2_b32 v4, v0, v1 offset0:136 offset1:204
	v_and_b32_e32 v0, 0xffff, v2
	v_lshrrev_b32_e32 v1, 16, v2
	v_lshl_or_b32 v0, v6, 16, v0
	v_and_or_b32 v1, v6, s59, v1
	v_add_u32_e32 v2, 0x8c00, v9
	ds_write2_b32 v2, v0, v1 offset0:16 offset1:84
	v_and_b32_e32 v0, 0xffff, v3
	v_lshrrev_b32_e32 v1, 16, v3
	v_lshl_or_b32 v0, v7, 16, v0
	v_and_or_b32 v1, v7, s59, v1
	ds_write2_b32 v2, v0, v1 offset0:152 offset1:220
	s_waitcnt vmcnt(2)
	v_mov_b64_e32 v[0:1], v[194:195]
	v_mov_b64_e32 v[2:3], v[196:197]
	v_mov_b64_e32 v[4:5], v[198:199]
	v_mov_b64_e32 v[6:7], v[200:201]
	v_and_b32_e32 v8, 0xffff, v0
	v_lshrrev_b32_e32 v0, 16, v0
	v_lshl_or_b32 v8, v4, 16, v8
	v_and_or_b32 v0, v4, s59, v0
	v_add_u32_e32 v4, 0x8800, v169
	ds_write2_b32 v4, v8, v0 offset1:68
	v_and_b32_e32 v0, 0xffff, v1
	v_lshrrev_b32_e32 v1, 16, v1
	v_lshl_or_b32 v0, v5, 16, v0
	v_and_or_b32 v1, v5, s59, v1
	ds_write2_b32 v4, v0, v1 offset0:136 offset1:204
	v_and_b32_e32 v0, 0xffff, v2
	v_lshrrev_b32_e32 v1, 16, v2
	v_lshl_or_b32 v0, v6, 16, v0
	v_and_or_b32 v1, v6, s59, v1
	v_add_u32_e32 v2, 0x8c00, v169
	ds_write2_b32 v2, v0, v1 offset0:16 offset1:84
	v_and_b32_e32 v0, 0xffff, v3
	v_lshrrev_b32_e32 v1, 16, v3
	v_lshl_or_b32 v0, v7, 16, v0
	v_and_or_b32 v1, v7, s59, v1
	ds_write2_b32 v2, v0, v1 offset0:152 offset1:220
	s_mov_b64 s[4:5], s[80:81]
	s_nop 0
	v_readlane_b32 s72, v252, 12
	v_readlane_b32 s82, v252, 22
	v_readlane_b32 s83, v252, 23
	s_add_u32 s52, s82, s0
	s_addc_u32 s53, s83, 0
	s_add_u32 s66, s55, s0
	s_addc_u32 s67, s64, 0
	v_readlane_b32 s80, v252, 20
	v_readlane_b32 s81, v252, 21
	s_add_u32 s0, s10, s0
	s_mov_b64 s[80:81], s[4:5]
	s_addc_u32 s4, s11, 0
	s_add_u32 s10, s0, 0x17100000
	s_movk_i32 s0, 0x2800
	s_addc_u32 s11, s4, 0
	v_readlane_b32 s76, v252, 16
	v_readlane_b32 s77, v252, 17
	v_readlane_b32 s78, v252, 18
	v_readlane_b32 s79, v252, 19
	v_readlane_b32 s84, v252, 24
	v_readlane_b32 s85, v252, 25
	v_readlane_b32 s86, v252, 26
	v_readlane_b32 s87, v252, 27
	v_readlane_b32 s84, v254, 51
	v_readlane_b32 s76, v254, 47
	v_readlane_b32 s78, v254, 45
	v_readlane_b32 s72, v254, 57
	v_readlane_b32 s85, v254, 52
	s_mov_b32 s87, 0xf800000
	v_readlane_b32 s86, v254, 50
	v_readlane_b32 s77, v254, 48
	v_readlane_b32 s79, v254, 46
	v_readlane_b32 s83, v254, 49
	v_readlane_b32 s73, v252, 13
	v_readlane_b32 s74, v252, 14
	v_readlane_b32 s75, v252, 15
	v_mov_b64_e32 v[132:133], s[66:67]
	v_lshlrev_b32_e32 v135, 2, v68
	v_lshlrev_b32_e32 v136, 2, v96
	v_lshlrev_b32_e32 v137, 2, v98
	v_or_b32_e32 v134, s54, v68
	v_mad_u64_u32 v[250:251], vcc, v134, s0, v[132:133]
	v_lshl_add_u64 v[250:251], v[250:251], 0, v[130:131]
	global_load_dword v242, v135, s[52:53]
	global_load_dwordx2 v[210:211], v[250:251], off
	global_load_dwordx2 v[212:213], v[250:251], off offset:32
	v_or_b32_e32 v134, s54, v100
	v_mad_u64_u32 v[250:251], vcc, v134, s0, v[132:133]
	v_lshl_add_u64 v[250:251], v[250:251], 0, v[130:131]
	global_load_dword v243, v135, s[52:53] offset:64
	global_load_dwordx2 v[214:215], v[250:251], off
	global_load_dwordx2 v[216:217], v[250:251], off offset:32
	v_or_b32_e32 v134, s54, v102
	v_mad_u64_u32 v[250:251], vcc, v134, s0, v[132:133]
	v_lshl_add_u64 v[250:251], v[250:251], 0, v[130:131]
	global_load_dword v244, v135, s[52:53] offset:128
	global_load_dwordx2 v[218:219], v[250:251], off
	global_load_dwordx2 v[220:221], v[250:251], off offset:32
	v_or_b32_e32 v134, s54, v96
	v_mad_u64_u32 v[250:251], vcc, v134, s0, v[132:133]
	v_lshl_add_u64 v[250:251], v[250:251], 0, v[130:131]
	global_load_dword v245, v136, s[52:53]
	global_load_dwordx2 v[222:223], v[250:251], off
	global_load_dwordx2 v[224:225], v[250:251], off offset:32
	v_or_b32_e32 v134, s54, v104
	v_mad_u64_u32 v[250:251], vcc, v134, s0, v[132:133]
	v_lshl_add_u64 v[250:251], v[250:251], 0, v[130:131]
	global_load_dword v246, v135, s[52:53] offset:256
	global_load_dwordx2 v[226:227], v[250:251], off
	global_load_dwordx2 v[228:229], v[250:251], off offset:32
	v_or_b32_e32 v134, s54, v106
	v_mad_u64_u32 v[250:251], vcc, v134, s0, v[132:133]
	v_lshl_add_u64 v[250:251], v[250:251], 0, v[130:131]
	global_load_dword v247, v135, s[52:53] offset:320
	global_load_dwordx2 v[230:231], v[250:251], off
	global_load_dwordx2 v[232:233], v[250:251], off offset:32
	v_or_b32_e32 v134, s54, v108
	v_mad_u64_u32 v[250:251], vcc, v134, s0, v[132:133]
	v_lshl_add_u64 v[250:251], v[250:251], 0, v[130:131]
	global_load_dword v248, v135, s[52:53] offset:384
	global_load_dwordx2 v[234:235], v[250:251], off
	global_load_dwordx2 v[236:237], v[250:251], off offset:32
	v_or_b32_e32 v134, s54, v98
	v_mad_u64_u32 v[250:251], vcc, v134, s0, v[132:133]
	v_lshl_add_u64 v[250:251], v[250:251], 0, v[130:131]
	global_load_dword v249, v137, s[52:53]
	global_load_dwordx2 v[238:239], v[250:251], off
	global_load_dwordx2 v[240:241], v[250:251], off offset:32
	s_waitcnt vmcnt(24)
	v_mov_b64_e32 v[0:1], v[202:203]
	v_mov_b64_e32 v[2:3], v[204:205]
	v_mov_b64_e32 v[4:5], v[206:207]
	v_mov_b64_e32 v[6:7], v[208:209]
	v_and_b32_e32 v8, 0xffff, v0
	v_lshrrev_b32_e32 v0, 16, v0
	v_lshl_or_b32 v8, v4, 16, v8
	v_and_or_b32 v0, v4, s59, v0
	v_add_u32_e32 v4, 0x8800, v170
	ds_write2_b32 v4, v8, v0 offset1:68
	v_and_b32_e32 v0, 0xffff, v1
	v_lshrrev_b32_e32 v1, 16, v1
	v_lshl_or_b32 v0, v5, 16, v0
	v_and_or_b32 v1, v5, s59, v1
	ds_write2_b32 v4, v0, v1 offset0:136 offset1:204
	v_and_b32_e32 v0, 0xffff, v2
	v_lshrrev_b32_e32 v1, 16, v2
	v_lshl_or_b32 v0, v6, 16, v0
	v_and_or_b32 v1, v6, s59, v1
	v_add_u32_e32 v2, 0x8c00, v170
	ds_write2_b32 v2, v0, v1 offset0:16 offset1:84
	v_and_b32_e32 v0, 0xffff, v3
	v_lshrrev_b32_e32 v1, 16, v3
	v_lshl_or_b32 v0, v7, 16, v0
	v_and_or_b32 v1, v7, s59, v1
	ds_write2_b32 v2, v0, v1 offset0:152 offset1:220
	s_waitcnt lgkmcnt(0)
	s_barrier
	ds_read_b128 v[0:3], v171 offset:34816
	ds_read_b128 v[4:7], v171 offset:39168
	ds_read_b128 v[8:11], v152
	ds_read_b128 v[16:19], v36
	s_waitcnt lgkmcnt(1)
	v_mfma_f32_16x16x32_bf16 v[60:63], v[0:3], v[8:11], 0
	ds_read_b128 v[24:27], v152 offset:17408
	ds_read_b128 v[32:35], v152 offset:21760
	v_mfma_f32_16x16x32_bf16 v[56:59], v[4:7], v[8:11], 0
	ds_read_b128 v[8:11], v152 offset:4352
	s_waitcnt lgkmcnt(0)
	v_mfma_f32_16x16x32_bf16 v[52:55], v[0:3], v[8:11], 0
	v_mfma_f32_16x16x32_bf16 v[48:51], v[4:7], v[8:11], 0
	ds_read_b128 v[8:11], v152 offset:8704
	v_mfma_f32_16x16x32_bf16 v[132:135], v[0:3], v[32:35], 0
	v_mfma_f32_16x16x32_bf16 v[136:139], v[4:7], v[32:35], 0
	ds_read_b128 v[32:35], v152 offset:26112
	s_waitcnt lgkmcnt(0)
	v_mfma_f32_16x16x32_bf16 v[140:143], v[0:3], v[32:35], 0
	v_mfma_f32_16x16x32_bf16 v[144:147], v[4:7], v[32:35], 0
	ds_read_b128 v[32:35], v172
	v_mfma_f32_16x16x32_bf16 v[12:15], v[0:3], v[8:11], 0
	v_mfma_f32_16x16x32_bf16 v[8:11], v[4:7], v[8:11], 0
	v_mfma_f32_16x16x32_bf16 v[20:23], v[0:3], v[16:19], 0
	v_mfma_f32_16x16x32_bf16 v[16:19], v[4:7], v[16:19], 0
	v_mfma_f32_16x16x32_bf16 v[28:31], v[0:3], v[24:27], 0
	v_mfma_f32_16x16x32_bf16 v[24:27], v[4:7], v[24:27], 0
	s_waitcnt lgkmcnt(0)
	v_mfma_f32_16x16x32_bf16 v[0:3], v[0:3], v[32:35], 0
	v_mfma_f32_16x16x32_bf16 v[4:7], v[4:7], v[32:35], 0
	ds_read_b128 v[148:151], v171 offset:34880
	ds_read_b128 v[158:161], v171 offset:39232
	ds_read_b128 v[32:35], v152 offset:8768
	s_waitcnt lgkmcnt(0)
	v_mfma_f32_16x16x32_bf16 v[40:43], v[158:161], v[32:35], v[8:11]
	s_nop 2
	ds_read_b128 v[8:11], v36 offset:64
	v_mfma_f32_16x16x32_bf16 v[44:47], v[148:151], v[32:35], v[12:15]
	s_waitcnt lgkmcnt(0)
	v_mfma_f32_16x16x32_bf16 v[36:39], v[148:151], v[8:11], v[20:23]
	v_mfma_f32_16x16x32_bf16 v[32:35], v[158:161], v[8:11], v[16:19]
	ds_read_b128 v[8:11], v152 offset:17472
	s_nop 1
	ds_read_b128 v[16:19], v152 offset:21824
	s_waitcnt lgkmcnt(1)
	v_mfma_f32_16x16x32_bf16 v[12:15], v[148:151], v[8:11], v[28:31]
	v_mfma_f32_16x16x32_bf16 v[8:11], v[158:161], v[8:11], v[24:27]
	s_nop 2
	ds_read_b128 v[24:27], v152 offset:26176
	s_waitcnt lgkmcnt(1)
	v_mfma_f32_16x16x32_bf16 v[20:23], v[148:151], v[16:19], v[132:135]
	v_mfma_f32_16x16x32_bf16 v[16:19], v[158:161], v[16:19], v[136:139]
	s_waitcnt lgkmcnt(0)
	v_mfma_f32_16x16x32_bf16 v[132:135], v[148:151], v[24:27], v[140:143]
	v_mfma_f32_16x16x32_bf16 v[136:139], v[158:161], v[24:27], v[144:147]
	ds_read_b128 v[24:27], v172 offset:64
	s_waitcnt lgkmcnt(0)
	v_mfma_f32_16x16x32_bf16 v[0:3], v[148:151], v[24:27], v[0:3]
	v_mfma_f32_16x16x32_bf16 v[4:7], v[158:161], v[24:27], v[4:7]
	ds_read_b128 v[140:143], v171 offset:34944
	ds_read_b128 v[144:147], v171 offset:39296
	ds_read_b128 v[24:27], v152 offset:17536
	s_waitcnt lgkmcnt(0)
	v_mfma_f32_16x16x32_bf16 v[28:31], v[140:143], v[24:27], v[12:15]
	v_mfma_f32_16x16x32_bf16 v[24:27], v[144:147], v[24:27], v[8:11]
	s_nop 2
	ds_read_b128 v[8:11], v152 offset:21888
	s_waitcnt lgkmcnt(0)
	v_mfma_f32_16x16x32_bf16 v[20:23], v[140:143], v[8:11], v[20:23]
	v_mfma_f32_16x16x32_bf16 v[16:19], v[144:147], v[8:11], v[16:19]
	ds_read_b128 v[8:11], v152 offset:26240
	s_waitcnt lgkmcnt(0)
	v_mfma_f32_16x16x32_bf16 v[12:15], v[140:143], v[8:11], v[132:135]
	s_nop 2
	ds_read_b128 v[132:135], v172 offset:128
	v_mfma_f32_16x16x32_bf16 v[8:11], v[144:147], v[8:11], v[136:139]
	s_waitcnt lgkmcnt(0)
	v_mfma_f32_16x16x32_bf16 v[0:3], v[140:143], v[132:135], v[0:3]
	v_mfma_f32_16x16x32_bf16 v[132:135], v[144:147], v[132:135], v[4:7]
	s_nop 2
	ds_read_b128 v[4:7], v171 offset:35008
	ds_read_b128 v[136:139], v171 offset:39360
	ds_read_b128 v[140:143], v152 offset:26304
	s_waitcnt lgkmcnt(0)
	v_mfma_f32_16x16x32_bf16 v[12:15], v[4:7], v[140:143], v[12:15]
	v_mfma_f32_16x16x32_bf16 v[8:11], v[136:139], v[140:143], v[8:11]
	ds_read_b128 v[140:143], v172 offset:192
	s_waitcnt lgkmcnt(0)
	v_mfma_f32_16x16x32_bf16 v[4:7], v[4:7], v[140:143], v[0:3]
	v_mfma_f32_16x16x32_bf16 v[0:3], v[136:139], v[140:143], v[132:135]
	s_waitcnt vmcnt(0)
	s_nop 7
	v_or_b32_e32 v138, s54, v68
	v_lshlrev_b32_e32 v152, 12, v138
	s_nop 0
	v_mov_b64_e32 v[132:133], s[66:67]
	v_mad_u64_u32 v[136:137], s[64:65], v138, s0, v[132:133]
	v_lshlrev_b32_e32 v135, 2, v68
	v_lshl_add_u64 v[136:137], v[136:137], 0, v[130:131]
	v_mov_b32_e32 v134, v242
	v_mov_b64_e32 v[140:141], v[210:211]
	v_lshl_add_u64 v[138:139], s[10:11], 0, v[152:153]
	v_pk_add_f32 v[60:61], v[60:61], v[134:135] op_sel_hi:[1,0]
	v_lshlrev_b32_e32 v142, 16, v140
	v_and_b32_e32 v143, 0xffff0000, v140
	v_lshlrev_b32_e32 v140, 16, v141
	v_and_b32_e32 v141, 0xffff0000, v141
	v_pk_add_f32 v[62:63], v[62:63], v[134:135] op_sel_hi:[1,0]
	v_pk_mul_f32 v[60:61], v[60:61], v[142:143]
	v_pk_mul_f32 v[62:63], v[62:63], v[140:141]
	v_cvt_pk_bf16_f32 v60, v60, v61
	v_cvt_pk_bf16_f32 v61, v62, v63
	v_lshl_add_u64 v[62:63], v[138:139], 0, v[130:131]
	global_store_dwordx2 v[62:63], v[60:61], off
	s_nop 1
	v_mov_b64_e32 v[60:61], v[212:213]
	v_pk_add_f32 v[56:57], v[56:57], v[134:135] op_sel_hi:[1,0]
	v_pk_add_f32 v[58:59], v[58:59], v[134:135] op_sel_hi:[1,0]
	v_lshlrev_b32_e32 v136, 16, v60
	v_and_b32_e32 v137, 0xffff0000, v60
	v_lshlrev_b32_e32 v60, 16, v61
	v_and_b32_e32 v61, 0xffff0000, v61
	v_pk_mul_f32 v[56:57], v[56:57], v[136:137]
	v_pk_mul_f32 v[58:59], v[58:59], v[60:61]
	v_cvt_pk_bf16_f32 v56, v56, v57
	v_cvt_pk_bf16_f32 v57, v58, v59
	global_store_dwordx2 v[62:63], v[56:57], off offset:32
	s_nop 1
	v_or_b32_e32 v57, s54, v100
	v_mad_u64_u32 v[58:59], s[64:65], v57, s0, v[132:133]
	v_lshl_add_u64 v[58:59], v[58:59], 0, v[130:131]
	v_mov_b32_e32 v56, v243
	v_mov_b64_e32 v[62:63], v[214:215]
	v_lshlrev_b32_e32 v152, 12, v57
	v_lshl_add_u64 v[60:61], s[10:11], 0, v[152:153]
	v_pk_add_f32 v[52:53], v[52:53], v[56:57] op_sel_hi:[1,0]
	v_lshlrev_b32_e32 v136, 16, v62
	v_and_b32_e32 v137, 0xffff0000, v62
	v_lshlrev_b32_e32 v62, 16, v63
	v_and_b32_e32 v63, 0xffff0000, v63
	v_pk_add_f32 v[54:55], v[54:55], v[56:57] op_sel_hi:[1,0]
	v_pk_mul_f32 v[52:53], v[52:53], v[136:137]
	v_pk_mul_f32 v[54:55], v[54:55], v[62:63]
	v_cvt_pk_bf16_f32 v52, v52, v53
	v_cvt_pk_bf16_f32 v53, v54, v55
	v_lshl_add_u64 v[54:55], v[60:61], 0, v[130:131]
	global_store_dwordx2 v[54:55], v[52:53], off
	s_nop 1
	v_mov_b64_e32 v[52:53], v[216:217]
	v_pk_add_f32 v[48:49], v[48:49], v[56:57] op_sel_hi:[1,0]
	v_pk_add_f32 v[50:51], v[50:51], v[56:57] op_sel_hi:[1,0]
	v_lshlrev_b32_e32 v58, 16, v52
	v_and_b32_e32 v59, 0xffff0000, v52
	v_lshlrev_b32_e32 v52, 16, v53
	v_and_b32_e32 v53, 0xffff0000, v53
	v_pk_mul_f32 v[48:49], v[48:49], v[58:59]
	v_pk_mul_f32 v[50:51], v[50:51], v[52:53]
	v_cvt_pk_bf16_f32 v48, v48, v49
	v_cvt_pk_bf16_f32 v49, v50, v51
	global_store_dwordx2 v[54:55], v[48:49], off offset:32
	s_nop 1
	v_or_b32_e32 v49, s54, v102
	v_mad_u64_u32 v[50:51], s[64:65], v49, s0, v[132:133]
	v_lshl_add_u64 v[50:51], v[50:51], 0, v[130:131]
	v_mov_b32_e32 v48, v244
	v_mov_b64_e32 v[54:55], v[218:219]
	v_lshlrev_b32_e32 v152, 12, v49
	v_lshl_add_u64 v[52:53], s[10:11], 0, v[152:153]
	v_pk_add_f32 v[44:45], v[44:45], v[48:49] op_sel_hi:[1,0]
	v_lshlrev_b32_e32 v56, 16, v54
	v_and_b32_e32 v57, 0xffff0000, v54
	v_lshlrev_b32_e32 v54, 16, v55
	v_and_b32_e32 v55, 0xffff0000, v55
	v_pk_add_f32 v[46:47], v[46:47], v[48:49] op_sel_hi:[1,0]
	v_pk_mul_f32 v[44:45], v[44:45], v[56:57]
	v_pk_mul_f32 v[46:47], v[46:47], v[54:55]
	v_cvt_pk_bf16_f32 v44, v44, v45
	v_cvt_pk_bf16_f32 v45, v46, v47
	v_lshl_add_u64 v[46:47], v[52:53], 0, v[130:131]
	global_store_dwordx2 v[46:47], v[44:45], off
	s_nop 1
	v_mov_b64_e32 v[44:45], v[220:221]
	v_pk_add_f32 v[40:41], v[40:41], v[48:49] op_sel_hi:[1,0]
	v_pk_add_f32 v[42:43], v[42:43], v[48:49] op_sel_hi:[1,0]
	v_lshlrev_b32_e32 v50, 16, v44
	v_and_b32_e32 v51, 0xffff0000, v44
	v_lshlrev_b32_e32 v44, 16, v45
	v_and_b32_e32 v45, 0xffff0000, v45
	v_pk_mul_f32 v[40:41], v[40:41], v[50:51]
	v_pk_mul_f32 v[42:43], v[42:43], v[44:45]
	v_cvt_pk_bf16_f32 v40, v40, v41
	v_cvt_pk_bf16_f32 v41, v42, v43
	global_store_dwordx2 v[46:47], v[40:41], off offset:32
	s_nop 1
	v_or_b32_e32 v41, s54, v96
	v_mad_u64_u32 v[42:43], s[64:65], v41, s0, v[132:133]
	v_lshlrev_b32_e32 v40, 2, v96
	v_lshl_add_u64 v[42:43], v[42:43], 0, v[130:131]
	v_mov_b32_e32 v40, v245
	v_lshlrev_b32_e32 v152, 12, v41
	v_mov_b64_e32 v[46:47], v[222:223]
	v_lshl_add_u64 v[44:45], s[10:11], 0, v[152:153]
	v_pk_add_f32 v[36:37], v[36:37], v[40:41] op_sel_hi:[1,0]
	v_pk_add_f32 v[38:39], v[38:39], v[40:41] op_sel_hi:[1,0]
	v_lshlrev_b32_e32 v48, 16, v46
	v_and_b32_e32 v49, 0xffff0000, v46
	v_lshlrev_b32_e32 v46, 16, v47
	v_and_b32_e32 v47, 0xffff0000, v47
	v_pk_mul_f32 v[36:37], v[36:37], v[48:49]
	v_pk_mul_f32 v[38:39], v[38:39], v[46:47]
	v_cvt_pk_bf16_f32 v36, v36, v37
	v_cvt_pk_bf16_f32 v37, v38, v39
	v_lshl_add_u64 v[38:39], v[44:45], 0, v[130:131]
	global_store_dwordx2 v[38:39], v[36:37], off
	s_nop 1
	v_mov_b64_e32 v[36:37], v[224:225]
	v_pk_add_f32 v[32:33], v[32:33], v[40:41] op_sel_hi:[1,0]
	v_pk_add_f32 v[34:35], v[34:35], v[40:41] op_sel_hi:[1,0]
	v_lshlrev_b32_e32 v42, 16, v36
	v_and_b32_e32 v43, 0xffff0000, v36
	v_lshlrev_b32_e32 v36, 16, v37
	v_and_b32_e32 v37, 0xffff0000, v37
	v_pk_mul_f32 v[32:33], v[32:33], v[42:43]
	v_pk_mul_f32 v[34:35], v[34:35], v[36:37]
	v_cvt_pk_bf16_f32 v32, v32, v33
	v_cvt_pk_bf16_f32 v33, v34, v35
	global_store_dwordx2 v[38:39], v[32:33], off offset:32
	s_nop 1
	v_or_b32_e32 v33, s54, v104
	v_mad_u64_u32 v[34:35], s[64:65], v33, s0, v[132:133]
	v_lshl_add_u64 v[34:35], v[34:35], 0, v[130:131]
	v_mov_b32_e32 v32, v246
	v_mov_b64_e32 v[38:39], v[226:227]
	v_lshlrev_b32_e32 v152, 12, v33
	v_lshl_add_u64 v[36:37], s[10:11], 0, v[152:153]
	v_pk_add_f32 v[28:29], v[28:29], v[32:33] op_sel_hi:[1,0]
	v_lshlrev_b32_e32 v40, 16, v38
	v_and_b32_e32 v41, 0xffff0000, v38
	v_lshlrev_b32_e32 v38, 16, v39
	v_and_b32_e32 v39, 0xffff0000, v39
	v_pk_add_f32 v[30:31], v[30:31], v[32:33] op_sel_hi:[1,0]
	v_pk_mul_f32 v[28:29], v[28:29], v[40:41]
	v_pk_mul_f32 v[30:31], v[30:31], v[38:39]
	v_cvt_pk_bf16_f32 v28, v28, v29
	v_cvt_pk_bf16_f32 v29, v30, v31
	v_lshl_add_u64 v[30:31], v[36:37], 0, v[130:131]
	global_store_dwordx2 v[30:31], v[28:29], off
	s_nop 1
	v_mov_b64_e32 v[28:29], v[228:229]
	v_pk_add_f32 v[24:25], v[24:25], v[32:33] op_sel_hi:[1,0]
	v_pk_add_f32 v[26:27], v[26:27], v[32:33] op_sel_hi:[1,0]
	v_lshlrev_b32_e32 v34, 16, v28
	v_and_b32_e32 v35, 0xffff0000, v28
	v_lshlrev_b32_e32 v28, 16, v29
	v_and_b32_e32 v29, 0xffff0000, v29
	v_pk_mul_f32 v[24:25], v[24:25], v[34:35]
	v_pk_mul_f32 v[26:27], v[26:27], v[28:29]
	v_cvt_pk_bf16_f32 v24, v24, v25
	v_cvt_pk_bf16_f32 v25, v26, v27
	global_store_dwordx2 v[30:31], v[24:25], off offset:32
	s_nop 1
	v_or_b32_e32 v25, s54, v106
	v_mad_u64_u32 v[26:27], s[64:65], v25, s0, v[132:133]
	v_lshl_add_u64 v[26:27], v[26:27], 0, v[130:131]
	v_mov_b32_e32 v24, v247
	v_mov_b64_e32 v[30:31], v[230:231]
	v_lshlrev_b32_e32 v152, 12, v25
	v_lshl_add_u64 v[28:29], s[10:11], 0, v[152:153]
	v_pk_add_f32 v[20:21], v[20:21], v[24:25] op_sel_hi:[1,0]
	v_lshlrev_b32_e32 v32, 16, v30
	v_and_b32_e32 v33, 0xffff0000, v30
	v_lshlrev_b32_e32 v30, 16, v31
	v_and_b32_e32 v31, 0xffff0000, v31
	v_pk_add_f32 v[22:23], v[22:23], v[24:25] op_sel_hi:[1,0]
	v_pk_mul_f32 v[20:21], v[20:21], v[32:33]
	v_pk_mul_f32 v[22:23], v[22:23], v[30:31]
	v_cvt_pk_bf16_f32 v20, v20, v21
	v_cvt_pk_bf16_f32 v21, v22, v23
	v_lshl_add_u64 v[22:23], v[28:29], 0, v[130:131]
	global_store_dwordx2 v[22:23], v[20:21], off
	s_nop 1
	v_mov_b64_e32 v[20:21], v[232:233]
	v_pk_add_f32 v[16:17], v[16:17], v[24:25] op_sel_hi:[1,0]
	v_pk_add_f32 v[18:19], v[18:19], v[24:25] op_sel_hi:[1,0]
	v_lshlrev_b32_e32 v26, 16, v20
	v_and_b32_e32 v27, 0xffff0000, v20
	v_lshlrev_b32_e32 v20, 16, v21
	v_and_b32_e32 v21, 0xffff0000, v21
	v_pk_mul_f32 v[16:17], v[16:17], v[26:27]
	v_pk_mul_f32 v[18:19], v[18:19], v[20:21]
	v_cvt_pk_bf16_f32 v16, v16, v17
	v_cvt_pk_bf16_f32 v17, v18, v19
	global_store_dwordx2 v[22:23], v[16:17], off offset:32
	s_nop 1
	v_or_b32_e32 v17, s54, v108
	v_mad_u64_u32 v[18:19], s[64:65], v17, s0, v[132:133]
	v_lshl_add_u64 v[18:19], v[18:19], 0, v[130:131]
	v_mov_b32_e32 v16, v248
	v_mov_b64_e32 v[22:23], v[234:235]
	v_lshlrev_b32_e32 v152, 12, v17
	v_lshl_add_u64 v[20:21], s[10:11], 0, v[152:153]
	v_pk_add_f32 v[12:13], v[12:13], v[16:17] op_sel_hi:[1,0]
	v_lshlrev_b32_e32 v24, 16, v22
	v_and_b32_e32 v25, 0xffff0000, v22
	v_lshlrev_b32_e32 v22, 16, v23
	v_and_b32_e32 v23, 0xffff0000, v23
	v_pk_add_f32 v[14:15], v[14:15], v[16:17] op_sel_hi:[1,0]
	v_pk_mul_f32 v[12:13], v[12:13], v[24:25]
	v_pk_mul_f32 v[14:15], v[14:15], v[22:23]
	v_cvt_pk_bf16_f32 v12, v12, v13
	v_cvt_pk_bf16_f32 v13, v14, v15
	v_lshl_add_u64 v[14:15], v[20:21], 0, v[130:131]
	global_store_dwordx2 v[14:15], v[12:13], off
	s_nop 1
	v_mov_b64_e32 v[12:13], v[236:237]
	v_pk_add_f32 v[8:9], v[8:9], v[16:17] op_sel_hi:[1,0]
	v_pk_add_f32 v[10:11], v[10:11], v[16:17] op_sel_hi:[1,0]
	v_lshlrev_b32_e32 v18, 16, v12
	v_and_b32_e32 v19, 0xffff0000, v12
	v_lshlrev_b32_e32 v12, 16, v13
	v_and_b32_e32 v13, 0xffff0000, v13
	v_pk_mul_f32 v[8:9], v[8:9], v[18:19]
	v_pk_mul_f32 v[10:11], v[10:11], v[12:13]
	v_cvt_pk_bf16_f32 v8, v8, v9
	v_cvt_pk_bf16_f32 v9, v10, v11
	global_store_dwordx2 v[14:15], v[8:9], off offset:32
	s_nop 1
	v_lshlrev_b32_e32 v8, 2, v98
	v_or_b32_e32 v9, s54, v98
	v_mov_b32_e32 v8, v249
	v_mad_u64_u32 v[12:13], s[52:53], v9, s0, v[132:133]
	v_lshl_add_u64 v[12:13], v[12:13], 0, v[130:131]
	v_mov_b64_e32 v[14:15], v[238:239]
	v_lshlrev_b32_e32 v152, 12, v9
	v_lshl_add_u64 v[10:11], s[10:11], 0, v[152:153]
	v_pk_add_f32 v[4:5], v[4:5], v[8:9] op_sel_hi:[1,0]
	v_pk_add_f32 v[6:7], v[6:7], v[8:9] op_sel_hi:[1,0]
	v_pk_add_f32 v[0:1], v[0:1], v[8:9] op_sel_hi:[1,0]
	v_pk_add_f32 v[2:3], v[2:3], v[8:9] op_sel_hi:[1,0]
	v_lshlrev_b32_e32 v16, 16, v14
	v_and_b32_e32 v17, 0xffff0000, v14
	v_lshlrev_b32_e32 v14, 16, v15
	v_and_b32_e32 v15, 0xffff0000, v15
	v_pk_mul_f32 v[4:5], v[4:5], v[16:17]
	v_pk_mul_f32 v[6:7], v[6:7], v[14:15]
	v_cvt_pk_bf16_f32 v4, v4, v5
	v_cvt_pk_bf16_f32 v5, v6, v7
	v_lshl_add_u64 v[6:7], v[10:11], 0, v[130:131]
	global_store_dwordx2 v[6:7], v[4:5], off
	s_nop 1
	v_mov_b64_e32 v[4:5], v[240:241]
	v_lshlrev_b32_e32 v10, 16, v4
	v_and_b32_e32 v11, 0xffff0000, v4
	v_lshlrev_b32_e32 v4, 16, v5
	v_and_b32_e32 v5, 0xffff0000, v5
	v_pk_mul_f32 v[0:1], v[0:1], v[10:11]
	v_pk_mul_f32 v[2:3], v[2:3], v[4:5]
	v_cvt_pk_bf16_f32 v0, v0, v1
	v_cvt_pk_bf16_f32 v1, v2, v3
	global_store_dwordx2 v[6:7], v[0:1], off offset:32
	s_nop 1
